# adds hand-written batched-load residual epilogues (C2/C4) and C1 R2 prefetch
# speedup vs baseline: 1.0433x; 1.0433x over previous
; DI void residual_epilogue(const Params& p, const f32x16 (&acc)[2][2], int m0, int n0, int ct, const float* stats_in, const float* g_in, const float* b_in,
;                           const float* gate, float* stats_out, char* smem) {
;     ...
;     float v[32];
;     read_staged(v, smem);
;     const int R = m0 + hf * 64 + (tid >> 2);
;     const int col0 = n0 + (tid & 3) * 32;
;     float mean = 0.f, rstd = 1.f;
;     if (stats_in) row_stats(stats_in, R, mean, rstd);
;     float4* xp = (float4*)(p.X + (size_t)R * 1024 + col0);
;     const float4* xsrc = stats_in ? (const float4*)xp : (const float4*)(in_row(p, R) + col0);
;     float s0 = 0.f, s1 = 0.f;
; #pragma unroll
;     for (int i = 0; i < 8; ++i) {
;       float4 xv = xsrc[i];
;       float xin[4] = {xv.x, xv.y, xv.z, xv.w};
;       float o[4];
; #pragma unroll
;       for (int j = 0; j < 4; ++j) {
;         int cc = col0 + 4 * i + j;
;         float xi = xin[j];
;         if (stats_in) xi = (xi - mean) * rstd * g_in[cc] + b_in[cc];
;         float val = ALPHA * xi + gate[cc] * v[4 * i + j];
;         o[j] = val; s0 += val; s1 += val * val;
;       }
;       xp[i] = make_float4(o[0], o[1], o[2], o[3]);
;     }
;     s0 += __shfl_xor(s0, 1); s1 += __shfl_xor(s1, 1);
;     s0 += __shfl_xor(s0, 2); s1 += __shfl_xor(s1, 2);
;     if ((tid & 3) == 0) { stats_out[(size_t)R * 16 + ct * 2] = s0; stats_out[(size_t)R * 16 + ct * 2 + 1] = s1; }
.LBB0_88:
	v_lshlrev_b32_e32 v186, 2, v104
	v_mov_b32_e32 v187, v144
	v_lshl_add_u64 v[180:181], v[100:101], 0, v[186:187]
	global_load_dwordx4 v[198:201], v[180:181], off
	global_load_dwordx4 v[202:205], v[180:181], off offset:16
	global_load_dwordx4 v[206:209], v[180:181], off offset:32
	global_load_dwordx4 v[210:213], v[180:181], off offset:48
	global_load_dwordx4 v[224:227], v[180:181], off offset:64
	global_load_dwordx4 v[234:237], v[180:181], off offset:80
	global_load_dwordx4 v[238:241], v[180:181], off offset:96
	global_load_dwordx4 v[244:247], v[180:181], off offset:112
	global_load_dwordx4 v[112:115], v[110:111], off
	global_load_dwordx4 v[116:119], v[110:111], off offset:16
	global_load_dwordx4 v[120:123], v[110:111], off offset:32
	global_load_dwordx4 v[124:127], v[110:111], off offset:48
	global_load_dwordx4 v[128:131], v[110:111], off offset:64
	global_load_dwordx4 v[132:135], v[110:111], off offset:80
	global_load_dwordx4 v[136:139], v[110:111], off offset:96
	global_load_dwordx4 v[140:143], v[110:111], off offset:112
	v_lshl_add_u64 v[192:193], v[74:75], 0, v[186:187]
	v_mov_b32_e32 v174, 0
	v_mov_b32_e32 v175, 0
	s_and_b64 vcc, exec, s[36:37]
	s_cbranch_vccz .Lre1_ns
	global_load_dwordx4 v[146:149], v[108:109], off
	global_load_dwordx4 v[150:153], v[108:109], off offset:16
	global_load_dwordx4 v[154:157], v[108:109], off offset:32
	global_load_dwordx4 v[158:161], v[108:109], off offset:48
	global_load_dwordx4 v[162:165], v[106:107], off
	global_load_dwordx4 v[166:169], v[106:107], off offset:16
	global_load_dwordx4 v[170:173], v[106:107], off offset:32
	global_load_dwordx4 v[188:191], v[106:107], off offset:48
	s_waitcnt vmcnt(0) lgkmcnt(0)
	v_sub_f32_e32 v178, v198, v179
	v_mul_f32_e32 v178, v145, v178
	v_fma_f32 v198, v178, v146, v162
	v_sub_f32_e32 v178, v199, v179
	v_mul_f32_e32 v178, v145, v178
	v_fma_f32 v199, v178, v147, v163
	v_sub_f32_e32 v178, v200, v179
	v_mul_f32_e32 v178, v145, v178
	v_fma_f32 v200, v178, v148, v164
	v_sub_f32_e32 v178, v201, v179
	v_mul_f32_e32 v178, v145, v178
	v_fma_f32 v201, v178, v149, v165
	v_sub_f32_e32 v178, v202, v179
	v_mul_f32_e32 v178, v145, v178
	v_fma_f32 v202, v178, v150, v166
	v_sub_f32_e32 v178, v203, v179
	v_mul_f32_e32 v178, v145, v178
	v_fma_f32 v203, v178, v151, v167
	v_sub_f32_e32 v178, v204, v179
	v_mul_f32_e32 v178, v145, v178
	v_fma_f32 v204, v178, v152, v168
	v_sub_f32_e32 v178, v205, v179
	v_mul_f32_e32 v178, v145, v178
	v_fma_f32 v205, v178, v153, v169
	v_sub_f32_e32 v178, v206, v179
	v_mul_f32_e32 v178, v145, v178
	v_fma_f32 v206, v178, v154, v170
	v_sub_f32_e32 v178, v207, v179
	v_mul_f32_e32 v178, v145, v178
	v_fma_f32 v207, v178, v155, v171
	v_sub_f32_e32 v178, v208, v179
	v_mul_f32_e32 v178, v145, v178
	v_fma_f32 v208, v178, v156, v172
	v_sub_f32_e32 v178, v209, v179
	v_mul_f32_e32 v178, v145, v178
	v_fma_f32 v209, v178, v157, v173
	v_sub_f32_e32 v178, v210, v179
	v_mul_f32_e32 v178, v145, v178
	v_fma_f32 v210, v178, v158, v188
	v_sub_f32_e32 v178, v211, v179
	v_mul_f32_e32 v178, v145, v178
	v_fma_f32 v211, v178, v159, v189
	v_sub_f32_e32 v178, v212, v179
	v_mul_f32_e32 v178, v145, v178
	v_fma_f32 v212, v178, v160, v190
	v_sub_f32_e32 v178, v213, v179
	v_mul_f32_e32 v178, v145, v178
	v_fma_f32 v213, v178, v161, v191
	global_load_dwordx4 v[146:149], v[108:109], off offset:64
	global_load_dwordx4 v[150:153], v[108:109], off offset:80
	global_load_dwordx4 v[154:157], v[108:109], off offset:96
	global_load_dwordx4 v[158:161], v[108:109], off offset:112
	global_load_dwordx4 v[162:165], v[106:107], off offset:64
	global_load_dwordx4 v[166:169], v[106:107], off offset:80
	global_load_dwordx4 v[170:173], v[106:107], off offset:96
	global_load_dwordx4 v[188:191], v[106:107], off offset:112
	v_mul_f32_e32 v96, v96, v112
	v_fmac_f32_e32 v96, v196, v198
	v_add_f32_e32 v174, v174, v96
	v_fmac_f32_e32 v175, v96, v96
	v_mul_f32_e32 v97, v97, v113
	v_fmac_f32_e32 v97, v196, v199
	v_add_f32_e32 v174, v174, v97
	v_fmac_f32_e32 v175, v97, v97
	v_mul_f32_e32 v98, v98, v114
	v_fmac_f32_e32 v98, v196, v200
	v_add_f32_e32 v174, v174, v98
	v_fmac_f32_e32 v175, v98, v98
	v_mul_f32_e32 v99, v99, v115
	v_fmac_f32_e32 v99, v196, v201
	v_add_f32_e32 v174, v174, v99
	v_fmac_f32_e32 v175, v99, v99
	v_mul_f32_e32 v92, v92, v116
	v_fmac_f32_e32 v92, v196, v202
	v_add_f32_e32 v174, v174, v92
	v_fmac_f32_e32 v175, v92, v92
	v_mul_f32_e32 v93, v93, v117
	v_fmac_f32_e32 v93, v196, v203
	v_add_f32_e32 v174, v174, v93
	v_fmac_f32_e32 v175, v93, v93
	v_mul_f32_e32 v94, v94, v118
	v_fmac_f32_e32 v94, v196, v204
	v_add_f32_e32 v174, v174, v94
	v_fmac_f32_e32 v175, v94, v94
	v_mul_f32_e32 v95, v95, v119
	v_fmac_f32_e32 v95, v196, v205
	v_add_f32_e32 v174, v174, v95
	v_fmac_f32_e32 v175, v95, v95
	v_mul_f32_e32 v88, v88, v120
	v_fmac_f32_e32 v88, v196, v206
	v_add_f32_e32 v174, v174, v88
	v_fmac_f32_e32 v175, v88, v88
	v_mul_f32_e32 v89, v89, v121
	v_fmac_f32_e32 v89, v196, v207
	v_add_f32_e32 v174, v174, v89
	v_fmac_f32_e32 v175, v89, v89
	v_mul_f32_e32 v90, v90, v122
	v_fmac_f32_e32 v90, v196, v208
	v_add_f32_e32 v174, v174, v90
	v_fmac_f32_e32 v175, v90, v90
	v_mul_f32_e32 v91, v91, v123
	v_fmac_f32_e32 v91, v196, v209
	v_add_f32_e32 v174, v174, v91
	v_fmac_f32_e32 v175, v91, v91
	v_mul_f32_e32 v84, v84, v124
	v_fmac_f32_e32 v84, v196, v210
	v_add_f32_e32 v174, v174, v84
	v_fmac_f32_e32 v175, v84, v84
	v_mul_f32_e32 v85, v85, v125
	v_fmac_f32_e32 v85, v196, v211
	v_add_f32_e32 v174, v174, v85
	v_fmac_f32_e32 v175, v85, v85
	v_mul_f32_e32 v86, v86, v126
	v_fmac_f32_e32 v86, v196, v212
	v_add_f32_e32 v174, v174, v86
	v_fmac_f32_e32 v175, v86, v86
	v_mul_f32_e32 v87, v87, v127
	v_fmac_f32_e32 v87, v196, v213
	v_add_f32_e32 v174, v174, v87
	v_fmac_f32_e32 v175, v87, v87
	global_store_dwordx4 v[192:193], v[96:99], off
	global_store_dwordx4 v[192:193], v[92:95], off offset:16
	global_store_dwordx4 v[192:193], v[88:91], off offset:32
	global_store_dwordx4 v[192:193], v[84:87], off offset:48
	s_waitcnt vmcnt(4)
; DI void residual_epilogue(const Params& p, const f32x16 (&acc)[2][2], int m0, int n0, int ct, const float* stats_in, const float* g_in, const float* b_in,
;                           const float* gate, float* stats_out, char* smem) {
;     ...
; #pragma unroll
;     for (int i = 0; i < 8; ++i) {
;       float4 xv = xsrc[i];
;       float xin[4] = {xv.x, xv.y, xv.z, xv.w};
;       float o[4];
; #pragma unroll
;       for (int j = 0; j < 4; ++j) {
;         int cc = col0 + 4 * i + j;
;         float xi = xin[j];
;         if (stats_in) xi = (xi - mean) * rstd * g_in[cc] + b_in[cc];
;         float val = ALPHA * xi + gate[cc] * v[4 * i + j];
;         o[j] = val; s0 += val; s1 += val * val;
;       }
;       xp[i] = make_float4(o[0], o[1], o[2], o[3]);
	v_sub_f32_e32 v178, v224, v179
	v_mul_f32_e32 v178, v145, v178
	v_fma_f32 v224, v178, v146, v162
	v_sub_f32_e32 v178, v225, v179
	v_mul_f32_e32 v178, v145, v178
	v_fma_f32 v225, v178, v147, v163
	v_sub_f32_e32 v178, v226, v179
	v_mul_f32_e32 v178, v145, v178
	v_fma_f32 v226, v178, v148, v164
	v_sub_f32_e32 v178, v227, v179
	v_mul_f32_e32 v178, v145, v178
	v_fma_f32 v227, v178, v149, v165
	v_sub_f32_e32 v178, v234, v179
	v_mul_f32_e32 v178, v145, v178
	v_fma_f32 v234, v178, v150, v166
	v_sub_f32_e32 v178, v235, v179
	v_mul_f32_e32 v178, v145, v178
	v_fma_f32 v235, v178, v151, v167
	v_sub_f32_e32 v178, v236, v179
	v_mul_f32_e32 v178, v145, v178
	v_fma_f32 v236, v178, v152, v168
	v_sub_f32_e32 v178, v237, v179
	v_mul_f32_e32 v178, v145, v178
	v_fma_f32 v237, v178, v153, v169
	v_sub_f32_e32 v178, v238, v179
	v_mul_f32_e32 v178, v145, v178
	v_fma_f32 v238, v178, v154, v170
	v_sub_f32_e32 v178, v239, v179
	v_mul_f32_e32 v178, v145, v178
	v_fma_f32 v239, v178, v155, v171
	v_sub_f32_e32 v178, v240, v179
	v_mul_f32_e32 v178, v145, v178
	v_fma_f32 v240, v178, v156, v172
	v_sub_f32_e32 v178, v241, v179
	v_mul_f32_e32 v178, v145, v178
	v_fma_f32 v241, v178, v157, v173
	v_sub_f32_e32 v178, v244, v179
	v_mul_f32_e32 v178, v145, v178
	v_fma_f32 v244, v178, v158, v188
	v_sub_f32_e32 v178, v245, v179
	v_mul_f32_e32 v178, v145, v178
	v_fma_f32 v245, v178, v159, v189
	v_sub_f32_e32 v178, v246, v179
	v_mul_f32_e32 v178, v145, v178
	v_fma_f32 v246, v178, v160, v190
	v_sub_f32_e32 v178, v247, v179
	v_mul_f32_e32 v178, v145, v178
	v_fma_f32 v247, v178, v161, v191
	v_mul_f32_e32 v80, v80, v128
	v_fmac_f32_e32 v80, v196, v224
	v_add_f32_e32 v174, v174, v80
	v_fmac_f32_e32 v175, v80, v80
	v_mul_f32_e32 v81, v81, v129
	v_fmac_f32_e32 v81, v196, v225
	v_add_f32_e32 v174, v174, v81
	v_fmac_f32_e32 v175, v81, v81
	v_mul_f32_e32 v82, v82, v130
	v_fmac_f32_e32 v82, v196, v226
	v_add_f32_e32 v174, v174, v82
	v_fmac_f32_e32 v175, v82, v82
	v_mul_f32_e32 v83, v83, v131
	v_fmac_f32_e32 v83, v196, v227
	v_add_f32_e32 v174, v174, v83
	v_fmac_f32_e32 v175, v83, v83
	v_mul_f32_e32 v76, v76, v132
	v_fmac_f32_e32 v76, v196, v234
	v_add_f32_e32 v174, v174, v76
	v_fmac_f32_e32 v175, v76, v76
	v_mul_f32_e32 v77, v77, v133
	v_fmac_f32_e32 v77, v196, v235
	v_add_f32_e32 v174, v174, v77
	v_fmac_f32_e32 v175, v77, v77
	v_mul_f32_e32 v78, v78, v134
	v_fmac_f32_e32 v78, v196, v236
	v_add_f32_e32 v174, v174, v78
	v_fmac_f32_e32 v175, v78, v78
	v_mul_f32_e32 v79, v79, v135
	v_fmac_f32_e32 v79, v196, v237
	v_add_f32_e32 v174, v174, v79
	v_fmac_f32_e32 v175, v79, v79
	v_mul_f32_e32 v68, v68, v136
	v_fmac_f32_e32 v68, v196, v238
	v_add_f32_e32 v174, v174, v68
	v_fmac_f32_e32 v175, v68, v68
	v_mul_f32_e32 v69, v69, v137
	v_fmac_f32_e32 v69, v196, v239
	v_add_f32_e32 v174, v174, v69
	v_fmac_f32_e32 v175, v69, v69
	v_mul_f32_e32 v70, v70, v138
	v_fmac_f32_e32 v70, v196, v240
	v_add_f32_e32 v174, v174, v70
	v_fmac_f32_e32 v175, v70, v70
	v_mul_f32_e32 v71, v71, v139
	v_fmac_f32_e32 v71, v196, v241
	v_add_f32_e32 v174, v174, v71
	v_fmac_f32_e32 v175, v71, v71
	v_mul_f32_e32 v64, v64, v140
	v_fmac_f32_e32 v64, v196, v244
	v_add_f32_e32 v174, v174, v64
	v_fmac_f32_e32 v175, v64, v64
	v_mul_f32_e32 v65, v65, v141
	v_fmac_f32_e32 v65, v196, v245
	v_add_f32_e32 v174, v174, v65
	v_fmac_f32_e32 v175, v65, v65
	v_mul_f32_e32 v66, v66, v142
	v_fmac_f32_e32 v66, v196, v246
	v_add_f32_e32 v174, v174, v66
	v_fmac_f32_e32 v175, v66, v66
	v_mul_f32_e32 v67, v67, v143
	v_fmac_f32_e32 v67, v196, v247
	v_add_f32_e32 v174, v174, v67
	v_fmac_f32_e32 v175, v67, v67
	global_store_dwordx4 v[192:193], v[80:83], off offset:64
	global_store_dwordx4 v[192:193], v[76:79], off offset:80
	global_store_dwordx4 v[192:193], v[68:71], off offset:96
	global_store_dwordx4 v[192:193], v[64:67], off offset:112
	s_branch .Lre1_red
; DI void residual_epilogue(const Params& p, const f32x16 (&acc)[2][2], int m0, int n0, int ct, const float* stats_in, const float* g_in, const float* b_in,
;                           const float* gate, float* stats_out, char* smem) {
;     ...
; #pragma unroll
;     for (int i = 0; i < 8; ++i) {
;       float4 xv = xsrc[i];
;       float xin[4] = {xv.x, xv.y, xv.z, xv.w};
;       float o[4];
; #pragma unroll
;       for (int j = 0; j < 4; ++j) {
;         int cc = col0 + 4 * i + j;
;         float xi = xin[j];
;         if (stats_in) xi = (xi - mean) * rstd * g_in[cc] + b_in[cc];
;         float val = ALPHA * xi + gate[cc] * v[4 * i + j];
;         o[j] = val; s0 += val; s1 += val * val;
;       }
;       xp[i] = make_float4(o[0], o[1], o[2], o[3]);
;     }
;     s0 += __shfl_xor(s0, 1); s1 += __shfl_xor(s1, 1);
;     s0 += __shfl_xor(s0, 2); s1 += __shfl_xor(s1, 2);
;     if ((tid & 3) == 0) { stats_out[(size_t)R * 16 + ct * 2] = s0; stats_out[(size_t)R * 16 + ct * 2 + 1] = s1; }
.Lre1_ns:
	s_waitcnt vmcnt(0) lgkmcnt(0)
	v_mul_f32_e32 v96, v96, v112
	v_fmac_f32_e32 v96, v196, v198
	v_add_f32_e32 v174, v174, v96
	v_fmac_f32_e32 v175, v96, v96
	v_mul_f32_e32 v97, v97, v113
	v_fmac_f32_e32 v97, v196, v199
	v_add_f32_e32 v174, v174, v97
	v_fmac_f32_e32 v175, v97, v97
	v_mul_f32_e32 v98, v98, v114
	v_fmac_f32_e32 v98, v196, v200
	v_add_f32_e32 v174, v174, v98
	v_fmac_f32_e32 v175, v98, v98
	v_mul_f32_e32 v99, v99, v115
	v_fmac_f32_e32 v99, v196, v201
	v_add_f32_e32 v174, v174, v99
	v_fmac_f32_e32 v175, v99, v99
	v_mul_f32_e32 v92, v92, v116
	v_fmac_f32_e32 v92, v196, v202
	v_add_f32_e32 v174, v174, v92
	v_fmac_f32_e32 v175, v92, v92
	v_mul_f32_e32 v93, v93, v117
	v_fmac_f32_e32 v93, v196, v203
	v_add_f32_e32 v174, v174, v93
	v_fmac_f32_e32 v175, v93, v93
	v_mul_f32_e32 v94, v94, v118
	v_fmac_f32_e32 v94, v196, v204
	v_add_f32_e32 v174, v174, v94
	v_fmac_f32_e32 v175, v94, v94
	v_mul_f32_e32 v95, v95, v119
	v_fmac_f32_e32 v95, v196, v205
	v_add_f32_e32 v174, v174, v95
	v_fmac_f32_e32 v175, v95, v95
	v_mul_f32_e32 v88, v88, v120
	v_fmac_f32_e32 v88, v196, v206
	v_add_f32_e32 v174, v174, v88
	v_fmac_f32_e32 v175, v88, v88
	v_mul_f32_e32 v89, v89, v121
	v_fmac_f32_e32 v89, v196, v207
	v_add_f32_e32 v174, v174, v89
	v_fmac_f32_e32 v175, v89, v89
	v_mul_f32_e32 v90, v90, v122
	v_fmac_f32_e32 v90, v196, v208
	v_add_f32_e32 v174, v174, v90
	v_fmac_f32_e32 v175, v90, v90
	v_mul_f32_e32 v91, v91, v123
	v_fmac_f32_e32 v91, v196, v209
	v_add_f32_e32 v174, v174, v91
	v_fmac_f32_e32 v175, v91, v91
	v_mul_f32_e32 v84, v84, v124
	v_fmac_f32_e32 v84, v196, v210
	v_add_f32_e32 v174, v174, v84
	v_fmac_f32_e32 v175, v84, v84
	v_mul_f32_e32 v85, v85, v125
	v_fmac_f32_e32 v85, v196, v211
	v_add_f32_e32 v174, v174, v85
	v_fmac_f32_e32 v175, v85, v85
	v_mul_f32_e32 v86, v86, v126
	v_fmac_f32_e32 v86, v196, v212
	v_add_f32_e32 v174, v174, v86
	v_fmac_f32_e32 v175, v86, v86
	v_mul_f32_e32 v87, v87, v127
	v_fmac_f32_e32 v87, v196, v213
	v_add_f32_e32 v174, v174, v87
	v_fmac_f32_e32 v175, v87, v87
	global_store_dwordx4 v[192:193], v[96:99], off
	global_store_dwordx4 v[192:193], v[92:95], off offset:16
	global_store_dwordx4 v[192:193], v[88:91], off offset:32
	global_store_dwordx4 v[192:193], v[84:87], off offset:48
	v_mul_f32_e32 v80, v80, v128
	v_fmac_f32_e32 v80, v196, v224
	v_add_f32_e32 v174, v174, v80
	v_fmac_f32_e32 v175, v80, v80
	v_mul_f32_e32 v81, v81, v129
	v_fmac_f32_e32 v81, v196, v225
	v_add_f32_e32 v174, v174, v81
	v_fmac_f32_e32 v175, v81, v81
	v_mul_f32_e32 v82, v82, v130
	v_fmac_f32_e32 v82, v196, v226
	v_add_f32_e32 v174, v174, v82
	v_fmac_f32_e32 v175, v82, v82
	v_mul_f32_e32 v83, v83, v131
	v_fmac_f32_e32 v83, v196, v227
	v_add_f32_e32 v174, v174, v83
	v_fmac_f32_e32 v175, v83, v83
	v_mul_f32_e32 v76, v76, v132
	v_fmac_f32_e32 v76, v196, v234
	v_add_f32_e32 v174, v174, v76
	v_fmac_f32_e32 v175, v76, v76
	v_mul_f32_e32 v77, v77, v133
	v_fmac_f32_e32 v77, v196, v235
	v_add_f32_e32 v174, v174, v77
	v_fmac_f32_e32 v175, v77, v77
	v_mul_f32_e32 v78, v78, v134
	v_fmac_f32_e32 v78, v196, v236
	v_add_f32_e32 v174, v174, v78
	v_fmac_f32_e32 v175, v78, v78
	v_mul_f32_e32 v79, v79, v135
	v_fmac_f32_e32 v79, v196, v237
	v_add_f32_e32 v174, v174, v79
	v_fmac_f32_e32 v175, v79, v79
	v_mul_f32_e32 v68, v68, v136
	v_fmac_f32_e32 v68, v196, v238
	v_add_f32_e32 v174, v174, v68
	v_fmac_f32_e32 v175, v68, v68
	v_mul_f32_e32 v69, v69, v137
	v_fmac_f32_e32 v69, v196, v239
	v_add_f32_e32 v174, v174, v69
	v_fmac_f32_e32 v175, v69, v69
	v_mul_f32_e32 v70, v70, v138
	v_fmac_f32_e32 v70, v196, v240
	v_add_f32_e32 v174, v174, v70
	v_fmac_f32_e32 v175, v70, v70
	v_mul_f32_e32 v71, v71, v139
	v_fmac_f32_e32 v71, v196, v241
	v_add_f32_e32 v174, v174, v71
	v_fmac_f32_e32 v175, v71, v71
	v_mul_f32_e32 v64, v64, v140
	v_fmac_f32_e32 v64, v196, v244
	v_add_f32_e32 v174, v174, v64
	v_fmac_f32_e32 v175, v64, v64
	v_mul_f32_e32 v65, v65, v141
	v_fmac_f32_e32 v65, v196, v245
	v_add_f32_e32 v174, v174, v65
	v_fmac_f32_e32 v175, v65, v65
	v_mul_f32_e32 v66, v66, v142
	v_fmac_f32_e32 v66, v196, v246
	v_add_f32_e32 v174, v174, v66
	v_fmac_f32_e32 v175, v66, v66
	v_mul_f32_e32 v67, v67, v143
	v_fmac_f32_e32 v67, v196, v247
	v_add_f32_e32 v174, v174, v67
	v_fmac_f32_e32 v175, v67, v67
	global_store_dwordx4 v[192:193], v[80:83], off offset:64
	global_store_dwordx4 v[192:193], v[76:79], off offset:80
	global_store_dwordx4 v[192:193], v[68:71], off offset:96
	global_store_dwordx4 v[192:193], v[64:67], off offset:112
.Lre1_red:
	s_nop 1
	v_add_f32_dpp v174, v174, v174 quad_perm:[1,0,3,2] row_mask:0xf bank_mask:0xf bound_ctrl:1
	v_add_f32_dpp v175, v175, v175 quad_perm:[1,0,3,2] row_mask:0xf bank_mask:0xf bound_ctrl:1
	s_nop 1
	v_add_f32_dpp v174, v174, v174 quad_perm:[2,3,0,1] row_mask:0xf bank_mask:0xf bound_ctrl:1
	v_add_f32_dpp v175, v175, v175 quad_perm:[2,3,0,1] row_mask:0xf bank_mask:0xf bound_ctrl:1
	s_and_saveexec_b64 s[4:5], s[6:7]
	s_cbranch_execz .LBB0_80
	v_lshl_add_u64 v[68:69], s[92:93], 0, v[176:177]
	global_store_dwordx2 v[68:69], v[174:175], off
	s_branch .LBB0_80

; DI unsigned pack2(float a, float b) { f2 v = {a, b}; bf2 c = __builtin_convertvector(v, bf2); return __builtin_bit_cast(unsigned, c); }
; DI void phaseC1_tile(const Params& p, int l, int t, char* smem) {
;     ...
;     for (int hf = 0; hf < 2; ++hf) {
;       stage_half(acc, hf, smem);
;       const int R = m0 + hf * 64 + (tid >> 2);
;       u16* dst = p.R2 + (size_t)R * 1024 + n0 + (tid & 3) * 32;
;       const float* srow = (const float*)smem + (tid >> 2) * 132 + (tid & 3) * 32;
; #pragma unroll 1
;       for (int c8 = 0; c8 < 4; ++c8) {
;         float4 g0 = *(const float4*)(srow + 8 * c8), g1 = *(const float4*)(srow + 8 * c8 + 4);
;         float o[8] = {g0.x, g0.y, g0.z, g0.w, g1.x, g1.y, g1.z, g1.w};
;         if (br > 0) {
;           float prev[8];
;           unpack8(*(const uint4*)(dst + 8 * c8), prev);
; #pragma unroll
;           for (int i = 0; i < 8; ++i) o[i] += prev[i];
;         }
;         uint4 q;
;         q.x = pack2(o[0], o[1]); q.y = pack2(o[2], o[3]); q.z = pack2(o[4], o[5]); q.w = pack2(o[6], o[7]);
;         *(uint4*)(dst + 8 * c8) = q;
;       }
;     }
.Lc1e_start:
	s_andn2_b64 vcc, exec, s[12:13]
	s_cbranch_vccnz .Lc1e_first
	global_load_dwordx4 v[224:227], v[8:9], off
	global_load_dwordx4 v[234:237], v[8:9], off offset:16
	global_load_dwordx4 v[238:241], v[8:9], off offset:32
	global_load_dwordx4 v[244:247], v[8:9], off offset:48
	ds_read_b128 v[4:7], v18
	ds_read_b128 v[0:3], v18 offset:16
	s_waitcnt vmcnt(3)
	v_lshlrev_b32_e32 v82, 16, v224
	v_and_b32_e32 v83, 0xffff0000, v224
	v_lshlrev_b32_e32 v78, 16, v225
	v_and_b32_e32 v79, 0xffff0000, v225
	v_lshlrev_b32_e32 v84, 16, v226
	v_and_b32_e32 v85, 0xffff0000, v226
	v_lshlrev_b32_e32 v80, 16, v227
	v_and_b32_e32 v81, 0xffff0000, v227
	s_waitcnt lgkmcnt(1)
	v_pk_add_f32 v[4:5], v[4:5], v[82:83]
	v_pk_add_f32 v[6:7], v[6:7], v[78:79]
	s_waitcnt lgkmcnt(0)
	v_pk_add_f32 v[0:1], v[0:1], v[84:85]
	v_pk_add_f32 v[2:3], v[2:3], v[80:81]
	v_cvt_pk_bf16_f32 v4, v4, v5
	v_cvt_pk_bf16_f32 v5, v6, v7
	v_cvt_pk_bf16_f32 v6, v0, v1
	v_cvt_pk_bf16_f32 v7, v2, v3
	global_store_dwordx4 v[8:9], v[4:7], off
	s_nop 1
	ds_read_b128 v[4:7], v18 offset:32
	ds_read_b128 v[0:3], v18 offset:48
	s_waitcnt vmcnt(3)
	v_lshlrev_b32_e32 v82, 16, v234
	v_and_b32_e32 v83, 0xffff0000, v234
	v_lshlrev_b32_e32 v78, 16, v235
	v_and_b32_e32 v79, 0xffff0000, v235
	v_lshlrev_b32_e32 v84, 16, v236
	v_and_b32_e32 v85, 0xffff0000, v236
	v_lshlrev_b32_e32 v80, 16, v237
	v_and_b32_e32 v81, 0xffff0000, v237
	s_waitcnt lgkmcnt(1)
	v_pk_add_f32 v[4:5], v[4:5], v[82:83]
	v_pk_add_f32 v[6:7], v[6:7], v[78:79]
	s_waitcnt lgkmcnt(0)
	v_pk_add_f32 v[0:1], v[0:1], v[84:85]
	v_pk_add_f32 v[2:3], v[2:3], v[80:81]
	v_cvt_pk_bf16_f32 v4, v4, v5
	v_cvt_pk_bf16_f32 v5, v6, v7
	v_cvt_pk_bf16_f32 v6, v0, v1
	v_cvt_pk_bf16_f32 v7, v2, v3
	global_store_dwordx4 v[8:9], v[4:7], off offset:16
	s_nop 1
	ds_read_b128 v[4:7], v18 offset:64
	ds_read_b128 v[0:3], v18 offset:80
	s_waitcnt vmcnt(3)
	v_lshlrev_b32_e32 v82, 16, v238
	v_and_b32_e32 v83, 0xffff0000, v238
	v_lshlrev_b32_e32 v78, 16, v239
	v_and_b32_e32 v79, 0xffff0000, v239
	v_lshlrev_b32_e32 v84, 16, v240
	v_and_b32_e32 v85, 0xffff0000, v240
	v_lshlrev_b32_e32 v80, 16, v241
	v_and_b32_e32 v81, 0xffff0000, v241
	s_waitcnt lgkmcnt(1)
	v_pk_add_f32 v[4:5], v[4:5], v[82:83]
	v_pk_add_f32 v[6:7], v[6:7], v[78:79]
	s_waitcnt lgkmcnt(0)
	v_pk_add_f32 v[0:1], v[0:1], v[84:85]
	v_pk_add_f32 v[2:3], v[2:3], v[80:81]
	v_cvt_pk_bf16_f32 v4, v4, v5
	v_cvt_pk_bf16_f32 v5, v6, v7
	v_cvt_pk_bf16_f32 v6, v0, v1
	v_cvt_pk_bf16_f32 v7, v2, v3
	global_store_dwordx4 v[8:9], v[4:7], off offset:32
	s_nop 1
	ds_read_b128 v[4:7], v18 offset:96
	ds_read_b128 v[0:3], v18 offset:112
	s_waitcnt vmcnt(3)
	v_lshlrev_b32_e32 v82, 16, v244
	v_and_b32_e32 v83, 0xffff0000, v244
	v_lshlrev_b32_e32 v78, 16, v245
	v_and_b32_e32 v79, 0xffff0000, v245
	v_lshlrev_b32_e32 v84, 16, v246
	v_and_b32_e32 v85, 0xffff0000, v246
	v_lshlrev_b32_e32 v80, 16, v247
	v_and_b32_e32 v81, 0xffff0000, v247
	s_waitcnt lgkmcnt(1)
	v_pk_add_f32 v[4:5], v[4:5], v[82:83]
	v_pk_add_f32 v[6:7], v[6:7], v[78:79]
	s_waitcnt lgkmcnt(0)
	v_pk_add_f32 v[0:1], v[0:1], v[84:85]
	v_pk_add_f32 v[2:3], v[2:3], v[80:81]
	v_cvt_pk_bf16_f32 v4, v4, v5
	v_cvt_pk_bf16_f32 v5, v6, v7
	v_cvt_pk_bf16_f32 v6, v0, v1
	v_cvt_pk_bf16_f32 v7, v2, v3
	global_store_dwordx4 v[8:9], v[4:7], off offset:48
	s_nop 1
	s_branch .LBB0_184
.Lc1e_first:
	ds_read_b128 v[4:7], v18
	ds_read_b128 v[0:3], v18 offset:16
	s_waitcnt lgkmcnt(1)
	v_cvt_pk_bf16_f32 v4, v4, v5
	v_cvt_pk_bf16_f32 v5, v6, v7
	s_waitcnt lgkmcnt(0)
	v_cvt_pk_bf16_f32 v6, v0, v1
	v_cvt_pk_bf16_f32 v7, v2, v3
	global_store_dwordx4 v[8:9], v[4:7], off
	s_nop 1
	ds_read_b128 v[4:7], v18 offset:32
	ds_read_b128 v[0:3], v18 offset:48
	s_waitcnt lgkmcnt(1)
	v_cvt_pk_bf16_f32 v4, v4, v5
	v_cvt_pk_bf16_f32 v5, v6, v7
	s_waitcnt lgkmcnt(0)
	v_cvt_pk_bf16_f32 v6, v0, v1
	v_cvt_pk_bf16_f32 v7, v2, v3
	global_store_dwordx4 v[8:9], v[4:7], off offset:16
	s_nop 1
	ds_read_b128 v[4:7], v18 offset:64
	ds_read_b128 v[0:3], v18 offset:80
	s_waitcnt lgkmcnt(1)
	v_cvt_pk_bf16_f32 v4, v4, v5
	v_cvt_pk_bf16_f32 v5, v6, v7
	s_waitcnt lgkmcnt(0)
	v_cvt_pk_bf16_f32 v6, v0, v1
	v_cvt_pk_bf16_f32 v7, v2, v3
	global_store_dwordx4 v[8:9], v[4:7], off offset:32
	s_nop 1
	ds_read_b128 v[4:7], v18 offset:96
	ds_read_b128 v[0:3], v18 offset:112
	s_waitcnt lgkmcnt(1)
	v_cvt_pk_bf16_f32 v4, v4, v5
	v_cvt_pk_bf16_f32 v5, v6, v7
	s_waitcnt lgkmcnt(0)
	v_cvt_pk_bf16_f32 v6, v0, v1
	v_cvt_pk_bf16_f32 v7, v2, v3
	global_store_dwordx4 v[8:9], v[4:7], off offset:48
	s_nop 1
	s_branch .LBB0_184

; DI void residual_epilogue(const Params& p, const f32x16 (&acc)[2][2], int m0, int n0, int ct, const float* stats_in, const float* g_in, const float* b_in,
;                           const float* gate, float* stats_out, char* smem) {
;     ...
;     float v[32];
;     read_staged(v, smem);
;     const int R = m0 + hf * 64 + (tid >> 2);
;     const int col0 = n0 + (tid & 3) * 32;
;     float mean = 0.f, rstd = 1.f;
;     if (stats_in) row_stats(stats_in, R, mean, rstd);
;     float4* xp = (float4*)(p.X + (size_t)R * 1024 + col0);
;     const float4* xsrc = stats_in ? (const float4*)xp : (const float4*)(in_row(p, R) + col0);
;     float s0 = 0.f, s1 = 0.f;
; #pragma unroll
;     for (int i = 0; i < 8; ++i) {
;       float4 xv = xsrc[i];
;       float xin[4] = {xv.x, xv.y, xv.z, xv.w};
;       float o[4];
; #pragma unroll
;       for (int j = 0; j < 4; ++j) {
;         int cc = col0 + 4 * i + j;
;         float xi = xin[j];
;         if (stats_in) xi = (xi - mean) * rstd * g_in[cc] + b_in[cc];
;         float val = ALPHA * xi + gate[cc] * v[4 * i + j];
;         o[j] = val; s0 += val; s1 += val * val;
;       }
;       xp[i] = make_float4(o[0], o[1], o[2], o[3]);
;     }
;     s0 += __shfl_xor(s0, 1); s1 += __shfl_xor(s1, 1);
;     s0 += __shfl_xor(s0, 2); s1 += __shfl_xor(s1, 2);
;     if ((tid & 3) == 0) { stats_out[(size_t)R * 16 + ct * 2] = s0; stats_out[(size_t)R * 16 + ct * 2 + 1] = s1; }
.LBB0_885:
	v_lshlrev_b32_e32 v186, 2, v104
	v_mov_b32_e32 v187, v144
	v_lshl_add_u64 v[180:181], v[100:101], 0, v[186:187]
	global_load_dwordx4 v[198:201], v[180:181], off
	global_load_dwordx4 v[202:205], v[180:181], off offset:16
	global_load_dwordx4 v[206:209], v[180:181], off offset:32
	global_load_dwordx4 v[210:213], v[180:181], off offset:48
	global_load_dwordx4 v[224:227], v[180:181], off offset:64
	global_load_dwordx4 v[234:237], v[180:181], off offset:80
	global_load_dwordx4 v[238:241], v[180:181], off offset:96
	global_load_dwordx4 v[244:247], v[180:181], off offset:112
	global_load_dwordx4 v[112:115], v[110:111], off
	global_load_dwordx4 v[116:119], v[110:111], off offset:16
	global_load_dwordx4 v[120:123], v[110:111], off offset:32
	global_load_dwordx4 v[124:127], v[110:111], off offset:48
	global_load_dwordx4 v[128:131], v[110:111], off offset:64
	global_load_dwordx4 v[132:135], v[110:111], off offset:80
	global_load_dwordx4 v[136:139], v[110:111], off offset:96
	global_load_dwordx4 v[140:143], v[110:111], off offset:112
	v_lshl_add_u64 v[192:193], v[78:79], 0, v[186:187]
	v_mov_b32_e32 v174, 0
	v_mov_b32_e32 v175, 0
	s_and_b64 vcc, exec, s[78:79]
	s_cbranch_vccz .Lre2_ns
	global_load_dwordx4 v[146:149], v[108:109], off
	global_load_dwordx4 v[150:153], v[108:109], off offset:16
	global_load_dwordx4 v[154:157], v[108:109], off offset:32
	global_load_dwordx4 v[158:161], v[108:109], off offset:48
	global_load_dwordx4 v[162:165], v[106:107], off
	global_load_dwordx4 v[166:169], v[106:107], off offset:16
	global_load_dwordx4 v[170:173], v[106:107], off offset:32
	global_load_dwordx4 v[188:191], v[106:107], off offset:48
	s_waitcnt vmcnt(0) lgkmcnt(0)
	v_sub_f32_e32 v178, v198, v179
	v_mul_f32_e32 v178, v145, v178
	v_fma_f32 v198, v178, v146, v162
	v_sub_f32_e32 v178, v199, v179
	v_mul_f32_e32 v178, v145, v178
	v_fma_f32 v199, v178, v147, v163
	v_sub_f32_e32 v178, v200, v179
	v_mul_f32_e32 v178, v145, v178
	v_fma_f32 v200, v178, v148, v164
	v_sub_f32_e32 v178, v201, v179
	v_mul_f32_e32 v178, v145, v178
	v_fma_f32 v201, v178, v149, v165
	v_sub_f32_e32 v178, v202, v179
	v_mul_f32_e32 v178, v145, v178
	v_fma_f32 v202, v178, v150, v166
	v_sub_f32_e32 v178, v203, v179
	v_mul_f32_e32 v178, v145, v178
	v_fma_f32 v203, v178, v151, v167
	v_sub_f32_e32 v178, v204, v179
	v_mul_f32_e32 v178, v145, v178
	v_fma_f32 v204, v178, v152, v168
	v_sub_f32_e32 v178, v205, v179
	v_mul_f32_e32 v178, v145, v178
	v_fma_f32 v205, v178, v153, v169
	v_sub_f32_e32 v178, v206, v179
	v_mul_f32_e32 v178, v145, v178
	v_fma_f32 v206, v178, v154, v170
	v_sub_f32_e32 v178, v207, v179
	v_mul_f32_e32 v178, v145, v178
	v_fma_f32 v207, v178, v155, v171
	v_sub_f32_e32 v178, v208, v179
	v_mul_f32_e32 v178, v145, v178
	v_fma_f32 v208, v178, v156, v172
	v_sub_f32_e32 v178, v209, v179
	v_mul_f32_e32 v178, v145, v178
	v_fma_f32 v209, v178, v157, v173
	v_sub_f32_e32 v178, v210, v179
	v_mul_f32_e32 v178, v145, v178
	v_fma_f32 v210, v178, v158, v188
	v_sub_f32_e32 v178, v211, v179
	v_mul_f32_e32 v178, v145, v178
	v_fma_f32 v211, v178, v159, v189
	v_sub_f32_e32 v178, v212, v179
	v_mul_f32_e32 v178, v145, v178
	v_fma_f32 v212, v178, v160, v190
	v_sub_f32_e32 v178, v213, v179
	v_mul_f32_e32 v178, v145, v178
	v_fma_f32 v213, v178, v161, v191
	global_load_dwordx4 v[146:149], v[108:109], off offset:64
	global_load_dwordx4 v[150:153], v[108:109], off offset:80
	global_load_dwordx4 v[154:157], v[108:109], off offset:96
	global_load_dwordx4 v[158:161], v[108:109], off offset:112
	global_load_dwordx4 v[162:165], v[106:107], off offset:64
	global_load_dwordx4 v[166:169], v[106:107], off offset:80
	global_load_dwordx4 v[170:173], v[106:107], off offset:96
	global_load_dwordx4 v[188:191], v[106:107], off offset:112
	v_mul_f32_e32 v96, v96, v112
	v_fmac_f32_e32 v96, v196, v198
	v_add_f32_e32 v174, v174, v96
	v_fmac_f32_e32 v175, v96, v96
	v_mul_f32_e32 v97, v97, v113
	v_fmac_f32_e32 v97, v196, v199
	v_add_f32_e32 v174, v174, v97
	v_fmac_f32_e32 v175, v97, v97
	v_mul_f32_e32 v98, v98, v114
	v_fmac_f32_e32 v98, v196, v200
	v_add_f32_e32 v174, v174, v98
	v_fmac_f32_e32 v175, v98, v98
	v_mul_f32_e32 v99, v99, v115
	v_fmac_f32_e32 v99, v196, v201
	v_add_f32_e32 v174, v174, v99
	v_fmac_f32_e32 v175, v99, v99
	v_mul_f32_e32 v92, v92, v116
	v_fmac_f32_e32 v92, v196, v202
	v_add_f32_e32 v174, v174, v92
	v_fmac_f32_e32 v175, v92, v92
	v_mul_f32_e32 v93, v93, v117
	v_fmac_f32_e32 v93, v196, v203
	v_add_f32_e32 v174, v174, v93
	v_fmac_f32_e32 v175, v93, v93
	v_mul_f32_e32 v94, v94, v118
	v_fmac_f32_e32 v94, v196, v204
	v_add_f32_e32 v174, v174, v94
	v_fmac_f32_e32 v175, v94, v94
	v_mul_f32_e32 v95, v95, v119
	v_fmac_f32_e32 v95, v196, v205
	v_add_f32_e32 v174, v174, v95
	v_fmac_f32_e32 v175, v95, v95
	v_mul_f32_e32 v88, v88, v120
	v_fmac_f32_e32 v88, v196, v206
	v_add_f32_e32 v174, v174, v88
	v_fmac_f32_e32 v175, v88, v88
	v_mul_f32_e32 v89, v89, v121
	v_fmac_f32_e32 v89, v196, v207
	v_add_f32_e32 v174, v174, v89
	v_fmac_f32_e32 v175, v89, v89
	v_mul_f32_e32 v90, v90, v122
	v_fmac_f32_e32 v90, v196, v208
	v_add_f32_e32 v174, v174, v90
	v_fmac_f32_e32 v175, v90, v90
	v_mul_f32_e32 v91, v91, v123
	v_fmac_f32_e32 v91, v196, v209
	v_add_f32_e32 v174, v174, v91
	v_fmac_f32_e32 v175, v91, v91
	v_mul_f32_e32 v84, v84, v124
	v_fmac_f32_e32 v84, v196, v210
	v_add_f32_e32 v174, v174, v84
	v_fmac_f32_e32 v175, v84, v84
	v_mul_f32_e32 v85, v85, v125
	v_fmac_f32_e32 v85, v196, v211
	v_add_f32_e32 v174, v174, v85
	v_fmac_f32_e32 v175, v85, v85
	v_mul_f32_e32 v86, v86, v126
	v_fmac_f32_e32 v86, v196, v212
	v_add_f32_e32 v174, v174, v86
	v_fmac_f32_e32 v175, v86, v86
	v_mul_f32_e32 v87, v87, v127
	v_fmac_f32_e32 v87, v196, v213
	v_add_f32_e32 v174, v174, v87
	v_fmac_f32_e32 v175, v87, v87
	global_store_dwordx4 v[192:193], v[96:99], off
	global_store_dwordx4 v[192:193], v[92:95], off offset:16
	global_store_dwordx4 v[192:193], v[88:91], off offset:32
	global_store_dwordx4 v[192:193], v[84:87], off offset:48
	s_waitcnt vmcnt(4)
; DI void residual_epilogue(const Params& p, const f32x16 (&acc)[2][2], int m0, int n0, int ct, const float* stats_in, const float* g_in, const float* b_in,
;                           const float* gate, float* stats_out, char* smem) {
;     ...
; #pragma unroll
;     for (int i = 0; i < 8; ++i) {
;       float4 xv = xsrc[i];
;       float xin[4] = {xv.x, xv.y, xv.z, xv.w};
;       float o[4];
; #pragma unroll
;       for (int j = 0; j < 4; ++j) {
;         int cc = col0 + 4 * i + j;
;         float xi = xin[j];
;         if (stats_in) xi = (xi - mean) * rstd * g_in[cc] + b_in[cc];
;         float val = ALPHA * xi + gate[cc] * v[4 * i + j];
;         o[j] = val; s0 += val; s1 += val * val;
;       }
;       xp[i] = make_float4(o[0], o[1], o[2], o[3]);
	v_sub_f32_e32 v178, v224, v179
	v_mul_f32_e32 v178, v145, v178
	v_fma_f32 v224, v178, v146, v162
	v_sub_f32_e32 v178, v225, v179
	v_mul_f32_e32 v178, v145, v178
	v_fma_f32 v225, v178, v147, v163
	v_sub_f32_e32 v178, v226, v179
	v_mul_f32_e32 v178, v145, v178
	v_fma_f32 v226, v178, v148, v164
	v_sub_f32_e32 v178, v227, v179
	v_mul_f32_e32 v178, v145, v178
	v_fma_f32 v227, v178, v149, v165
	v_sub_f32_e32 v178, v234, v179
	v_mul_f32_e32 v178, v145, v178
	v_fma_f32 v234, v178, v150, v166
	v_sub_f32_e32 v178, v235, v179
	v_mul_f32_e32 v178, v145, v178
	v_fma_f32 v235, v178, v151, v167
	v_sub_f32_e32 v178, v236, v179
	v_mul_f32_e32 v178, v145, v178
	v_fma_f32 v236, v178, v152, v168
	v_sub_f32_e32 v178, v237, v179
	v_mul_f32_e32 v178, v145, v178
	v_fma_f32 v237, v178, v153, v169
	v_sub_f32_e32 v178, v238, v179
	v_mul_f32_e32 v178, v145, v178
	v_fma_f32 v238, v178, v154, v170
	v_sub_f32_e32 v178, v239, v179
	v_mul_f32_e32 v178, v145, v178
	v_fma_f32 v239, v178, v155, v171
	v_sub_f32_e32 v178, v240, v179
	v_mul_f32_e32 v178, v145, v178
	v_fma_f32 v240, v178, v156, v172
	v_sub_f32_e32 v178, v241, v179
	v_mul_f32_e32 v178, v145, v178
	v_fma_f32 v241, v178, v157, v173
	v_sub_f32_e32 v178, v244, v179
	v_mul_f32_e32 v178, v145, v178
	v_fma_f32 v244, v178, v158, v188
	v_sub_f32_e32 v178, v245, v179
	v_mul_f32_e32 v178, v145, v178
	v_fma_f32 v245, v178, v159, v189
	v_sub_f32_e32 v178, v246, v179
	v_mul_f32_e32 v178, v145, v178
	v_fma_f32 v246, v178, v160, v190
	v_sub_f32_e32 v178, v247, v179
	v_mul_f32_e32 v178, v145, v178
	v_fma_f32 v247, v178, v161, v191
	v_mul_f32_e32 v80, v80, v128
	v_fmac_f32_e32 v80, v196, v224
	v_add_f32_e32 v174, v174, v80
	v_fmac_f32_e32 v175, v80, v80
	v_mul_f32_e32 v81, v81, v129
	v_fmac_f32_e32 v81, v196, v225
	v_add_f32_e32 v174, v174, v81
	v_fmac_f32_e32 v175, v81, v81
	v_mul_f32_e32 v82, v82, v130
	v_fmac_f32_e32 v82, v196, v226
	v_add_f32_e32 v174, v174, v82
	v_fmac_f32_e32 v175, v82, v82
	v_mul_f32_e32 v83, v83, v131
	v_fmac_f32_e32 v83, v196, v227
	v_add_f32_e32 v174, v174, v83
	v_fmac_f32_e32 v175, v83, v83
	v_mul_f32_e32 v72, v72, v132
	v_fmac_f32_e32 v72, v196, v234
	v_add_f32_e32 v174, v174, v72
	v_fmac_f32_e32 v175, v72, v72
	v_mul_f32_e32 v73, v73, v133
	v_fmac_f32_e32 v73, v196, v235
	v_add_f32_e32 v174, v174, v73
	v_fmac_f32_e32 v175, v73, v73
	v_mul_f32_e32 v74, v74, v134
	v_fmac_f32_e32 v74, v196, v236
	v_add_f32_e32 v174, v174, v74
	v_fmac_f32_e32 v175, v74, v74
	v_mul_f32_e32 v75, v75, v135
	v_fmac_f32_e32 v75, v196, v237
	v_add_f32_e32 v174, v174, v75
	v_fmac_f32_e32 v175, v75, v75
	v_mul_f32_e32 v68, v68, v136
	v_fmac_f32_e32 v68, v196, v238
	v_add_f32_e32 v174, v174, v68
	v_fmac_f32_e32 v175, v68, v68
	v_mul_f32_e32 v69, v69, v137
	v_fmac_f32_e32 v69, v196, v239
	v_add_f32_e32 v174, v174, v69
	v_fmac_f32_e32 v175, v69, v69
	v_mul_f32_e32 v70, v70, v138
	v_fmac_f32_e32 v70, v196, v240
	v_add_f32_e32 v174, v174, v70
	v_fmac_f32_e32 v175, v70, v70
	v_mul_f32_e32 v71, v71, v139
	v_fmac_f32_e32 v71, v196, v241
	v_add_f32_e32 v174, v174, v71
	v_fmac_f32_e32 v175, v71, v71
	v_mul_f32_e32 v64, v64, v140
	v_fmac_f32_e32 v64, v196, v244
	v_add_f32_e32 v174, v174, v64
	v_fmac_f32_e32 v175, v64, v64
	v_mul_f32_e32 v65, v65, v141
	v_fmac_f32_e32 v65, v196, v245
	v_add_f32_e32 v174, v174, v65
	v_fmac_f32_e32 v175, v65, v65
	v_mul_f32_e32 v66, v66, v142
	v_fmac_f32_e32 v66, v196, v246
	v_add_f32_e32 v174, v174, v66
	v_fmac_f32_e32 v175, v66, v66
	v_mul_f32_e32 v67, v67, v143
	v_fmac_f32_e32 v67, v196, v247
	v_add_f32_e32 v174, v174, v67
	v_fmac_f32_e32 v175, v67, v67
	global_store_dwordx4 v[192:193], v[80:83], off offset:64
	global_store_dwordx4 v[192:193], v[72:75], off offset:80
	global_store_dwordx4 v[192:193], v[68:71], off offset:96
	global_store_dwordx4 v[192:193], v[64:67], off offset:112
	s_branch .Lre2_red
; DI void residual_epilogue(const Params& p, const f32x16 (&acc)[2][2], int m0, int n0, int ct, const float* stats_in, const float* g_in, const float* b_in,
;                           const float* gate, float* stats_out, char* smem) {
;     ...
; #pragma unroll
;     for (int i = 0; i < 8; ++i) {
;       float4 xv = xsrc[i];
;       float xin[4] = {xv.x, xv.y, xv.z, xv.w};
;       float o[4];
; #pragma unroll
;       for (int j = 0; j < 4; ++j) {
;         int cc = col0 + 4 * i + j;
;         float xi = xin[j];
;         if (stats_in) xi = (xi - mean) * rstd * g_in[cc] + b_in[cc];
;         float val = ALPHA * xi + gate[cc] * v[4 * i + j];
;         o[j] = val; s0 += val; s1 += val * val;
;       }
;       xp[i] = make_float4(o[0], o[1], o[2], o[3]);
;     }
;     s0 += __shfl_xor(s0, 1); s1 += __shfl_xor(s1, 1);
;     s0 += __shfl_xor(s0, 2); s1 += __shfl_xor(s1, 2);
;     if ((tid & 3) == 0) { stats_out[(size_t)R * 16 + ct * 2] = s0; stats_out[(size_t)R * 16 + ct * 2 + 1] = s1; }
.Lre2_ns:
	s_waitcnt vmcnt(0) lgkmcnt(0)
	v_mul_f32_e32 v96, v96, v112
	v_fmac_f32_e32 v96, v196, v198
	v_add_f32_e32 v174, v174, v96
	v_fmac_f32_e32 v175, v96, v96
	v_mul_f32_e32 v97, v97, v113
	v_fmac_f32_e32 v97, v196, v199
	v_add_f32_e32 v174, v174, v97
	v_fmac_f32_e32 v175, v97, v97
	v_mul_f32_e32 v98, v98, v114
	v_fmac_f32_e32 v98, v196, v200
	v_add_f32_e32 v174, v174, v98
	v_fmac_f32_e32 v175, v98, v98
	v_mul_f32_e32 v99, v99, v115
	v_fmac_f32_e32 v99, v196, v201
	v_add_f32_e32 v174, v174, v99
	v_fmac_f32_e32 v175, v99, v99
	v_mul_f32_e32 v92, v92, v116
	v_fmac_f32_e32 v92, v196, v202
	v_add_f32_e32 v174, v174, v92
	v_fmac_f32_e32 v175, v92, v92
	v_mul_f32_e32 v93, v93, v117
	v_fmac_f32_e32 v93, v196, v203
	v_add_f32_e32 v174, v174, v93
	v_fmac_f32_e32 v175, v93, v93
	v_mul_f32_e32 v94, v94, v118
	v_fmac_f32_e32 v94, v196, v204
	v_add_f32_e32 v174, v174, v94
	v_fmac_f32_e32 v175, v94, v94
	v_mul_f32_e32 v95, v95, v119
	v_fmac_f32_e32 v95, v196, v205
	v_add_f32_e32 v174, v174, v95
	v_fmac_f32_e32 v175, v95, v95
	v_mul_f32_e32 v88, v88, v120
	v_fmac_f32_e32 v88, v196, v206
	v_add_f32_e32 v174, v174, v88
	v_fmac_f32_e32 v175, v88, v88
	v_mul_f32_e32 v89, v89, v121
	v_fmac_f32_e32 v89, v196, v207
	v_add_f32_e32 v174, v174, v89
	v_fmac_f32_e32 v175, v89, v89
	v_mul_f32_e32 v90, v90, v122
	v_fmac_f32_e32 v90, v196, v208
	v_add_f32_e32 v174, v174, v90
	v_fmac_f32_e32 v175, v90, v90
	v_mul_f32_e32 v91, v91, v123
	v_fmac_f32_e32 v91, v196, v209
	v_add_f32_e32 v174, v174, v91
	v_fmac_f32_e32 v175, v91, v91
	v_mul_f32_e32 v84, v84, v124
	v_fmac_f32_e32 v84, v196, v210
	v_add_f32_e32 v174, v174, v84
	v_fmac_f32_e32 v175, v84, v84
	v_mul_f32_e32 v85, v85, v125
	v_fmac_f32_e32 v85, v196, v211
	v_add_f32_e32 v174, v174, v85
	v_fmac_f32_e32 v175, v85, v85
	v_mul_f32_e32 v86, v86, v126
	v_fmac_f32_e32 v86, v196, v212
	v_add_f32_e32 v174, v174, v86
	v_fmac_f32_e32 v175, v86, v86
	v_mul_f32_e32 v87, v87, v127
	v_fmac_f32_e32 v87, v196, v213
	v_add_f32_e32 v174, v174, v87
	v_fmac_f32_e32 v175, v87, v87
	global_store_dwordx4 v[192:193], v[96:99], off
	global_store_dwordx4 v[192:193], v[92:95], off offset:16
	global_store_dwordx4 v[192:193], v[88:91], off offset:32
	global_store_dwordx4 v[192:193], v[84:87], off offset:48
	v_mul_f32_e32 v80, v80, v128
	v_fmac_f32_e32 v80, v196, v224
	v_add_f32_e32 v174, v174, v80
	v_fmac_f32_e32 v175, v80, v80
	v_mul_f32_e32 v81, v81, v129
	v_fmac_f32_e32 v81, v196, v225
	v_add_f32_e32 v174, v174, v81
	v_fmac_f32_e32 v175, v81, v81
	v_mul_f32_e32 v82, v82, v130
	v_fmac_f32_e32 v82, v196, v226
	v_add_f32_e32 v174, v174, v82
	v_fmac_f32_e32 v175, v82, v82
	v_mul_f32_e32 v83, v83, v131
	v_fmac_f32_e32 v83, v196, v227
	v_add_f32_e32 v174, v174, v83
	v_fmac_f32_e32 v175, v83, v83
	v_mul_f32_e32 v72, v72, v132
	v_fmac_f32_e32 v72, v196, v234
	v_add_f32_e32 v174, v174, v72
	v_fmac_f32_e32 v175, v72, v72
	v_mul_f32_e32 v73, v73, v133
	v_fmac_f32_e32 v73, v196, v235
	v_add_f32_e32 v174, v174, v73
	v_fmac_f32_e32 v175, v73, v73
	v_mul_f32_e32 v74, v74, v134
	v_fmac_f32_e32 v74, v196, v236
	v_add_f32_e32 v174, v174, v74
	v_fmac_f32_e32 v175, v74, v74
	v_mul_f32_e32 v75, v75, v135
	v_fmac_f32_e32 v75, v196, v237
	v_add_f32_e32 v174, v174, v75
	v_fmac_f32_e32 v175, v75, v75
	v_mul_f32_e32 v68, v68, v136
	v_fmac_f32_e32 v68, v196, v238
	v_add_f32_e32 v174, v174, v68
	v_fmac_f32_e32 v175, v68, v68
	v_mul_f32_e32 v69, v69, v137
	v_fmac_f32_e32 v69, v196, v239
	v_add_f32_e32 v174, v174, v69
	v_fmac_f32_e32 v175, v69, v69
	v_mul_f32_e32 v70, v70, v138
	v_fmac_f32_e32 v70, v196, v240
	v_add_f32_e32 v174, v174, v70
	v_fmac_f32_e32 v175, v70, v70
	v_mul_f32_e32 v71, v71, v139
	v_fmac_f32_e32 v71, v196, v241
	v_add_f32_e32 v174, v174, v71
	v_fmac_f32_e32 v175, v71, v71
	v_mul_f32_e32 v64, v64, v140
	v_fmac_f32_e32 v64, v196, v244
	v_add_f32_e32 v174, v174, v64
	v_fmac_f32_e32 v175, v64, v64
	v_mul_f32_e32 v65, v65, v141
	v_fmac_f32_e32 v65, v196, v245
	v_add_f32_e32 v174, v174, v65
	v_fmac_f32_e32 v175, v65, v65
	v_mul_f32_e32 v66, v66, v142
	v_fmac_f32_e32 v66, v196, v246
	v_add_f32_e32 v174, v174, v66
	v_fmac_f32_e32 v175, v66, v66
	v_mul_f32_e32 v67, v67, v143
	v_fmac_f32_e32 v67, v196, v247
	v_add_f32_e32 v174, v174, v67
	v_fmac_f32_e32 v175, v67, v67
	global_store_dwordx4 v[192:193], v[80:83], off offset:64
	global_store_dwordx4 v[192:193], v[72:75], off offset:80
	global_store_dwordx4 v[192:193], v[68:71], off offset:96
	global_store_dwordx4 v[192:193], v[64:67], off offset:112
.Lre2_red:
	s_nop 1
	v_add_f32_dpp v174, v174, v174 quad_perm:[1,0,3,2] row_mask:0xf bank_mask:0xf bound_ctrl:1
	v_add_f32_dpp v175, v175, v175 quad_perm:[1,0,3,2] row_mask:0xf bank_mask:0xf bound_ctrl:1
	s_nop 1
	v_add_f32_dpp v174, v174, v174 quad_perm:[2,3,0,1] row_mask:0xf bank_mask:0xf bound_ctrl:1
	v_add_f32_dpp v175, v175, v175 quad_perm:[2,3,0,1] row_mask:0xf bank_mask:0xf bound_ctrl:1
	s_and_saveexec_b64 s[4:5], s[6:7]
	s_cbranch_execz .LBB0_877
	v_lshl_add_u64 v[68:69], s[14:15], 0, v[176:177]
	global_store_dwordx2 v[68:69], v[174:175], off
	s_branch .LBB0_877
